# router logits loop: all 16 weight loads of a k-batch in flight (hand-scheduled), same MFMA order
# speedup vs baseline: 1.0005x; 1.0005x over previous
.LBB0_1158:
	v_lshl_or_b32 v94, s2, 7, v158
	v_lshl_or_b32 v232, s2, 8, v159
	v_add_lshl_u32 v100, v94, v171, 1
	v_add_lshl_u32 v94, v94, v157, 1
	v_add_u32_e32 v233, v161, v232
	v_add_u32_e32 v232, v160, v232
	global_load_dwordx4 v[50:53], v94, s[16:17] offset:0
	global_load_dwordx4 v[54:57], v94, s[18:19] offset:0
	global_load_dwordx4 v[58:61], v100, s[16:17] offset:0
	global_load_dwordx4 v[62:65], v100, s[18:19] offset:0
	global_load_dwordx4 v[66:69], v94, s[16:17] offset:64
	global_load_dwordx4 v[70:73], v94, s[18:19] offset:64
	global_load_dwordx4 v[74:77], v100, s[16:17] offset:64
	global_load_dwordx4 v[78:81], v100, s[18:19] offset:64
	global_load_dwordx4 v[82:85], v94, s[16:17] offset:128
	global_load_dwordx4 v[86:89], v94, s[18:19] offset:128
	global_load_dwordx4 v[90:93], v100, s[16:17] offset:128
	global_load_dwordx4 v[216:219], v100, s[18:19] offset:128
	global_load_dwordx4 v[220:223], v94, s[16:17] offset:192
	global_load_dwordx4 v[224:227], v94, s[18:19] offset:192
	global_load_dwordx4 v[228:231], v100, s[16:17] offset:192
	global_load_dwordx4 v[246:249], v100, s[18:19] offset:192
	s_mov_b32 s2, 1
	ds_read_b128 v[38:41], v232 offset:0
	ds_read_b128 v[42:45], v233 offset:0
	s_waitcnt vmcnt(12) lgkmcnt(0)
	v_mfma_f32_16x16x32_bf16 v[46:49], v[38:41], v[50:53], v[46:49]
	v_mfma_f32_16x16x32_bf16 v[34:37], v[38:41], v[58:61], v[34:37]
	v_mfma_f32_16x16x32_bf16 v[46:49], v[38:41], v[54:57], v[46:49]
	v_mfma_f32_16x16x32_bf16 v[34:37], v[38:41], v[62:65], v[34:37]
	v_mfma_f32_16x16x32_bf16 v[46:49], v[42:45], v[50:53], v[46:49]
	v_mfma_f32_16x16x32_bf16 v[34:37], v[42:45], v[58:61], v[34:37]
	ds_read_b128 v[38:41], v232 offset:64
	ds_read_b128 v[42:45], v233 offset:64
	s_waitcnt vmcnt(8) lgkmcnt(0)
	v_mfma_f32_16x16x32_bf16 v[46:49], v[38:41], v[66:69], v[46:49]
	v_mfma_f32_16x16x32_bf16 v[34:37], v[38:41], v[74:77], v[34:37]
	v_mfma_f32_16x16x32_bf16 v[46:49], v[38:41], v[70:73], v[46:49]
	v_mfma_f32_16x16x32_bf16 v[34:37], v[38:41], v[78:81], v[34:37]
	v_mfma_f32_16x16x32_bf16 v[46:49], v[42:45], v[66:69], v[46:49]
	v_mfma_f32_16x16x32_bf16 v[34:37], v[42:45], v[74:77], v[34:37]
	ds_read_b128 v[38:41], v232 offset:128
	ds_read_b128 v[42:45], v233 offset:128
	s_waitcnt vmcnt(4) lgkmcnt(0)
	v_mfma_f32_16x16x32_bf16 v[46:49], v[38:41], v[82:85], v[46:49]
	v_mfma_f32_16x16x32_bf16 v[34:37], v[38:41], v[90:93], v[34:37]
	v_mfma_f32_16x16x32_bf16 v[46:49], v[38:41], v[86:89], v[46:49]
	v_mfma_f32_16x16x32_bf16 v[34:37], v[38:41], v[216:219], v[34:37]
	v_mfma_f32_16x16x32_bf16 v[46:49], v[42:45], v[82:85], v[46:49]
	v_mfma_f32_16x16x32_bf16 v[34:37], v[42:45], v[90:93], v[34:37]
	ds_read_b128 v[38:41], v232 offset:192
	ds_read_b128 v[42:45], v233 offset:192
	s_waitcnt vmcnt(0) lgkmcnt(0)
	v_mfma_f32_16x16x32_bf16 v[46:49], v[38:41], v[220:223], v[46:49]
	v_mfma_f32_16x16x32_bf16 v[34:37], v[38:41], v[228:231], v[34:37]
	v_mfma_f32_16x16x32_bf16 v[46:49], v[38:41], v[224:227], v[46:49]
	v_mfma_f32_16x16x32_bf16 v[34:37], v[38:41], v[246:249], v[34:37]
	v_mfma_f32_16x16x32_bf16 v[46:49], v[42:45], v[220:223], v[46:49]
	v_mfma_f32_16x16x32_bf16 v[34:37], v[42:45], v[228:231], v[34:37]
	s_nop 3
	v_cndmask_b32_e64 v38, 0, 1, s[10:11]
	v_cmp_ne_u32_e32 vcc, 1, v38
	s_mov_b64 s[10:11], 0
	s_cbranch_vccz .LBB0_1158
	s_waitcnt lgkmcnt(0)
	s_barrier
	ds_write2_b32 v184, v46, v34 offset1:16
	ds_write2_b32 v184, v47, v35 offset0:32 offset1:48
	ds_write2_b32 v184, v48, v36 offset0:64 offset1:80
	ds_write2_b32 v184, v49, v37 offset0:96 offset1:112
	s_waitcnt lgkmcnt(0)
	s_barrier
	ds_read2st64_b32 v[34:35], v172 offset1:8
	ds_read2st64_b32 v[36:37], v172 offset0:16 offset1:24
	ds_read2st64_b32 v[38:39], v172 offset0:32 offset1:40
	s_waitcnt lgkmcnt(2)
	v_add_f32_e32 v34, v188, v34
	v_add_f32_e32 v40, v34, v35
	ds_read2st64_b32 v[34:35], v172 offset0:48 offset1:56
	s_waitcnt lgkmcnt(2)
	v_add_f32_e32 v36, v40, v36
	v_add_f32_e32 v36, v36, v37
	s_waitcnt lgkmcnt(1)
	v_add_f32_e32 v36, v36, v38
	v_add_f32_e32 v36, v36, v39
	s_waitcnt lgkmcnt(0)
	v_add_f32_e32 v34, v36, v34
	v_add_f32_e32 v34, v34, v35
	ds_write_b32 v173, v34
	s_waitcnt lgkmcnt(0)
	s_barrier
	ds_read_b32 v35, v185
	s_waitcnt lgkmcnt(0)
	v_max_f32_e32 v36, v35, v35
	s_waitcnt lgkmcnt(0)
	s_nop 1
	v_max_f32_dpp v34, v35, v36 quad_perm:[1,0,3,2] row_mask:0xf bank_mask:0xf
	s_waitcnt lgkmcnt(0)
	s_nop 1
	v_max_f32_dpp v34, v34, v34 quad_perm:[2,3,0,1] row_mask:0xf bank_mask:0xf
	s_waitcnt lgkmcnt(0)
	s_nop 1
	v_max_f32_dpp v34, v34, v34 row_half_mirror row_mask:0xf bank_mask:0xf
	s_waitcnt lgkmcnt(0)
	s_nop 1
	v_max_f32_dpp v34, v34, v34 row_mirror row_mask:0xf bank_mask:0xf
	ds_bpermute_b32 v36, v155, v34
	s_waitcnt lgkmcnt(0)
	v_max_f32_e32 v36, v36, v36
	v_max_f32_e32 v38, v34, v36
	v_cmp_eq_f32_e32 vcc, v35, v38
	s_nop 1
	v_mov_b32_e32 v34, vcc_hi
	v_mov_b32_e32 v36, vcc_lo
	v_cndmask_b32_e64 v34, v34, v36, s[6:7]
	v_ffbl_b32_e32 v34, v34
	v_cmp_ne_u32_e32 vcc, v1, v34
	s_nop 1
	v_cndmask_b32_e32 v36, v187, v35, vcc
	v_max_f32_e32 v37, v36, v36
	s_waitcnt lgkmcnt(0)
	s_nop 1
	v_max_f32_dpp v35, v36, v37 quad_perm:[1,0,3,2] row_mask:0xf bank_mask:0xf
	s_waitcnt lgkmcnt(0)
	s_nop 1
	v_max_f32_dpp v35, v35, v35 quad_perm:[2,3,0,1] row_mask:0xf bank_mask:0xf
	s_waitcnt lgkmcnt(0)
	s_nop 1
	v_max_f32_dpp v35, v35, v35 row_half_mirror row_mask:0xf bank_mask:0xf
	s_waitcnt lgkmcnt(0)
	s_nop 1
	v_max_f32_dpp v35, v35, v35 row_mirror row_mask:0xf bank_mask:0xf
	ds_bpermute_b32 v37, v155, v35
	s_waitcnt lgkmcnt(0)
	v_max_f32_e32 v37, v37, v37
	v_max_f32_e32 v39, v35, v37
	v_cmp_eq_f32_e32 vcc, v36, v39
	s_nop 1
	v_mov_b32_e32 v35, vcc_hi
	v_mov_b32_e32 v37, vcc_lo
	v_cndmask_b32_e64 v35, v35, v37, s[6:7]
	v_ffbl_b32_e32 v35, v35
	v_cmp_ne_u32_e32 vcc, v1, v35
	s_nop 1
	v_cndmask_b32_e32 v37, v187, v36, vcc
	v_max_f32_e32 v40, v37, v37
	s_waitcnt lgkmcnt(0)
	s_nop 1
	v_max_f32_dpp v36, v37, v40 quad_perm:[1,0,3,2] row_mask:0xf bank_mask:0xf
	s_waitcnt lgkmcnt(0)
	s_nop 1
	v_max_f32_dpp v36, v36, v36 quad_perm:[2,3,0,1] row_mask:0xf bank_mask:0xf
	s_waitcnt lgkmcnt(0)
	s_nop 1
	v_max_f32_dpp v36, v36, v36 row_half_mirror row_mask:0xf bank_mask:0xf
	s_waitcnt lgkmcnt(0)
	s_nop 1
	v_max_f32_dpp v36, v36, v36 row_mirror row_mask:0xf bank_mask:0xf
	ds_bpermute_b32 v40, v155, v36
	s_waitcnt lgkmcnt(0)
	v_max_f32_e32 v40, v40, v40
	v_max_f32_e32 v40, v36, v40
	v_cmp_eq_f32_e32 vcc, v37, v40
	s_nop 1
	v_mov_b32_e32 v36, vcc_hi
	v_mov_b32_e32 v41, vcc_lo
	v_cndmask_b32_e64 v36, v36, v41, s[6:7]
	v_ffbl_b32_e32 v36, v36
	v_cmp_ne_u32_e32 vcc, v1, v36
	s_nop 1
	v_cndmask_b32_e32 v37, v187, v37, vcc
	v_max_f32_e32 v42, v37, v37
	s_waitcnt lgkmcnt(0)
	s_nop 1
	v_max_f32_dpp v41, v37, v42 quad_perm:[1,0,3,2] row_mask:0xf bank_mask:0xf
	s_waitcnt lgkmcnt(0)
	s_nop 1
	v_max_f32_dpp v41, v41, v41 quad_perm:[2,3,0,1] row_mask:0xf bank_mask:0xf
	s_waitcnt lgkmcnt(0)
	s_nop 1
	v_max_f32_dpp v41, v41, v41 row_half_mirror row_mask:0xf bank_mask:0xf
	s_waitcnt lgkmcnt(0)
	s_nop 1
	v_max_f32_dpp v41, v41, v41 row_mirror row_mask:0xf bank_mask:0xf
	ds_bpermute_b32 v42, v155, v41
	s_waitcnt lgkmcnt(0)
	v_max_f32_e32 v42, v42, v42
	v_max_f32_e32 v41, v41, v42
	v_cmp_eq_f32_e32 vcc, v37, v41
	s_and_saveexec_b64 s[10:11], s[8:9]
	s_cbranch_execz .LBB0_1156
	v_mov_b32_e32 v37, vcc_hi
	v_mov_b32_e32 v43, vcc_lo
	v_cndmask_b32_e64 v37, v37, v43, s[6:7]
	v_sub_f32_e32 v43, v38, v38
	v_sub_f32_e32 v39, v39, v38
	v_mul_f32_e32 v43, 0x3fb8aa3b, v43
	v_mul_f32_e32 v39, 0x3fb8aa3b, v39
	v_exp_f32_e32 v44, v43
	v_exp_f32_e32 v45, v39
	v_sub_f32_e32 v39, v40, v38
	v_mul_f32_e32 v39, 0x3fb8aa3b, v39
	v_sub_f32_e32 v38, v41, v38
	v_exp_f32_e32 v40, v39
	v_mul_f32_e32 v38, 0x3fb8aa3b, v38
	v_exp_f32_e32 v41, v38
	v_add_f32_e32 v38, 0, v44
	v_add_f32_e32 v38, v38, v45
	v_add_f32_e32 v38, v38, v40
	v_add_f32_e32 v48, v38, v41
	v_div_scale_f32 v49, s[38:39], v48, v48, 1.0
	v_rcp_f32_e32 v50, v49
	v_add_u32_e32 v42, s35, v162
	v_ashrrev_i32_e32 v43, 31, v42
	v_lshlrev_b64 v[38:39], 4, v[42:43]
	v_lshl_add_u64 v[42:43], s[20:21], 0, v[38:39]
	v_lshl_add_u64 v[46:47], s[22:23], 0, v[38:39]
	v_fma_f32 v38, -v49, v50, 1.0
	v_fmac_f32_e32 v50, v38, v50
	v_div_scale_f32 v38, vcc, 1.0, v48, 1.0
	v_mul_f32_e32 v39, v38, v50
	v_fma_f32 v51, -v49, v39, v38
	v_fmac_f32_e32 v39, v51, v50
	v_fma_f32 v38, -v49, v39, v38
	v_div_fmas_f32 v38, v38, v50, v39
	v_div_fixup_f32 v38, v38, v48, 1.0
	v_ffbl_b32_e32 v37, v37
	v_pk_mul_f32 v[40:41], v[40:41], v[38:39] op_sel_hi:[1,0]
	v_pk_mul_f32 v[38:39], v[44:45], v[38:39] op_sel_hi:[1,0]
	global_store_dwordx4 v[42:43], v[34:37], off
	global_store_dwordx4 v[46:47], v[38:41], off
	s_nop 0
	v_lshl_add_u32 v34, v34, 2, s3
	ds_add_u32 v34, v186
	v_lshl_add_u32 v34, v35, 2, s3
	ds_add_u32 v34, v186
	v_lshl_add_u32 v34, v36, 2, s3
	ds_add_u32 v34, v186
	v_lshl_add_u32 v34, v37, 2, s3
	ds_add_u32 v34, v186
	s_branch .LBB0_1156
